# P4 read-once loads marked nt
# speedup vs baseline: 1.0045x; 1.0045x over previous
; DEVINL float bflo(unsigned u) { return __uint_as_float(u << 16); }
; DEVINL float bfhi(unsigned u) { return __uint_as_float(u & 0xffff0000u); }
; DEVINL float sigm(float x) { return 1.f / (1.f + __expf(-x)); }
; DEVINL void phase4(const Params& p) {
;     ...
;   for (int u = gw; u < T_ * 4; u += nw) {
;     const long t = u >> 2; const int h = u & 3;
;     const int c = h * 256 + lane * 4;
;     float4 o;
;     {
;       uint2 of = *(const uint2*)((const u16*)(ws + O_OSUM) + t * 1024 + c);
;       uint2 ob = *(const uint2*)((const u16*)(ws + O_OSUM) + (long)T_ * 1024 + t * 1024 + c);
;       o.x = bflo(of.x) + bflo(ob.x); o.y = bfhi(of.x) + bfhi(ob.x);
;       o.z = bflo(of.y) + bflo(ob.y); o.w = bfhi(of.y) + bfhi(ob.y);
;     }
;     float ss = o.x * o.x + o.y * o.y + o.z * o.z + o.w * o.w;
;     ss = allred64(ss);
;     const float rstd = rsqrtf(ss * (1.f / 256.f) + 1e-5f);
;     float4 ng = *(const float4*)(p.gla_norm_g + c);
;     uint2 gg = *(const uint2*)(cols + t * NCP + C_G + c);
;     float g0 = bflo(gg.x), g1 = bfhi(gg.x), g2 = bflo(gg.y), g3 = bfhi(gg.y);
;     float y0 = o.x * rstd * ng.x * (g0 * sigm(g0));
;     float y1 = o.y * rstd * ng.y * (g1 * sigm(g1));
;     float y2 = o.z * rstd * ng.z * (g2 * sigm(g2));
;     float y3 = o.w * rstd * ng.w * (g3 * sigm(g3));
;     *(uint2*)((u16*)(ws + O_YGLA) + t * 1024 + c) = make_uint2(pk2(y0, y1), pk2(y2, y3));
;   }
.LBB0_552:
	v_ashrrev_i32_e32 v16, 2, v10
	v_ashrrev_i32_e32 v17, 31, v16
	v_lshlrev_b64 v[18:19], 11, v[16:17]
	v_and_or_b32 v11, v7, s20, v6
	v_lshl_add_u64 v[20:21], s[92:93], 0, v[18:19]
	v_add_u32_e32 v10, s60, v10
	v_lshlrev_b32_e32 v0, 1, v11
	v_lshl_add_u64 v[22:23], s[14:15], 0, v[18:19]
	v_mad_i64_i32 v[16:17], s[0:1], v16, s21, v[20:21]
	v_lshlrev_b32_e32 v11, 2, v11
	v_cmp_lt_i32_e32 vcc, s24, v10
	v_lshl_add_u64 v[24:25], v[20:21], 0, v[0:1]
	v_lshl_add_u64 v[22:23], v[22:23], 0, v[0:1]
	v_lshl_add_u64 v[16:17], v[16:17], 0, v[0:1]
	global_load_dwordx4 v[12:15], v11, s[88:89] nt
	s_or_b64 s[18:19], vcc, s[18:19]
	global_load_dwordx2 v[20:21], v[24:25], off nt
	s_nop 0
	global_load_dwordx2 v[22:23], v[22:23], off nt
	v_add_co_u32_e32 v16, vcc, s22, v16
	v_lshl_add_u64 v[18:19], s[16:17], 0, v[18:19]
	s_nop 0
	v_addc_co_u32_e32 v17, vcc, 0, v17, vcc
	global_load_dwordx2 v[16:17], v[16:17], off nt
	v_lshl_add_u64 v[18:19], v[18:19], 0, v[0:1]
	v_mov_b32_e32 v32, v1
	v_mov_b32_e32 v33, v1
	v_add_u32_e32 v7, s3, v7
	s_waitcnt vmcnt(2)
	v_lshlrev_b32_e32 v24, 16, v20
	s_waitcnt vmcnt(1)
	v_lshlrev_b32_e32 v26, 16, v22
	v_and_b32_e32 v25, 0xffff0000, v20
	v_and_b32_e32 v27, 0xffff0000, v22
	v_lshlrev_b32_e32 v20, 16, v21
	v_lshlrev_b32_e32 v22, 16, v23
	v_and_b32_e32 v21, 0xffff0000, v21
	v_and_b32_e32 v23, 0xffff0000, v23
	v_pk_add_f32 v[20:21], v[20:21], v[22:23]
	v_pk_add_f32 v[22:23], v[24:25], v[26:27]
	s_waitcnt vmcnt(0)
	v_lshlrev_b32_e32 v24, 16, v16
	v_and_b32_e32 v25, 0xffff0000, v16
	v_pk_mul_f32 v[28:29], v[22:23], v[22:23]
	v_lshlrev_b32_e32 v16, 16, v17
	v_and_b32_e32 v17, 0xffff0000, v17
	v_pk_mul_f32 v[26:27], v[20:21], v[20:21]
	v_mul_f32_e32 v0, 0xbfb8aa3b, v24
	v_mul_f32_e32 v11, 0xbfb8aa3b, v25
	v_add_f32_e32 v30, v28, v29
	v_mul_f32_e32 v31, 0xbfb8aa3b, v16
	v_mul_f32_e32 v34, 0xbfb8aa3b, v17
	v_exp_f32_e32 v28, v0
	v_exp_f32_e32 v29, v11
	v_add_f32_e32 v0, v30, v26
	v_exp_f32_e32 v30, v31
	v_exp_f32_e32 v31, v34
	v_add_f32_e32 v0, v27, v0
	v_pk_add_f32 v[26:27], v[28:29], 1.0 op_sel_hi:[1,0]
	v_pk_add_f32 v[28:29], v[30:31], 1.0 op_sel_hi:[1,0]
	v_add_f32_dpp v0, v0, v0 quad_perm:[1,0,3,2] row_mask:0xf bank_mask:0xf bound_ctrl:1
	v_div_scale_f32 v11, s[0:1], v27, v27, 1.0
	s_nop 0
	v_add_f32_dpp v0, v0, v0 quad_perm:[2,3,0,1] row_mask:0xf bank_mask:0xf bound_ctrl:1
	v_div_scale_f32 v31, s[0:1], v26, v26, 1.0
	s_nop 0
	v_add_f32_dpp v0, v0, v0 row_half_mirror row_mask:0xf bank_mask:0xf bound_ctrl:1
	v_div_scale_f32 v35, s[6:7], v29, v29, 1.0
	s_nop 0
	v_add_f32_dpp v0, v0, v0 row_mirror row_mask:0xf bank_mask:0xf bound_ctrl:1
	v_div_scale_f32 v37, s[8:9], v28, v28, 1.0
	v_rcp_f32_e32 v39, v11
	v_mov_b32_dpp v32, v0 row_bcast:15 row_mask:0xa bank_mask:0xf
	v_rcp_f32_e32 v40, v31
	v_rcp_f32_e32 v41, v35
	v_rcp_f32_e32 v42, v37
	v_add_f32_e32 v0, v0, v32
	v_fma_f32 v32, -v11, v39, 1.0
	v_div_scale_f32 v30, vcc, 1.0, v27, 1.0
	v_mov_b32_dpp v33, v0 row_bcast:31 row_mask:0xc bank_mask:0xf
	v_add_f32_e32 v0, v0, v33
	v_fma_f32 v33, -v31, v40, 1.0
	v_readlane_b32 s10, v0, 63
	v_fma_f32 v0, -v35, v41, 1.0
	v_fma_f32 v43, -v37, v42, 1.0
	v_fmac_f32_e32 v39, v32, v39
	v_fma_f32 v32, s10, v9, v8
	v_div_scale_f32 v34, s[0:1], 1.0, v26, 1.0
	v_fmac_f32_e32 v40, v33, v40
	v_fmac_f32_e32 v41, v0, v41
	v_fmac_f32_e32 v42, v43, v42
	v_mul_f32_e32 v0, v30, v39
	v_mul_f32_e32 v43, 0x4b800000, v32
	v_cmp_gt_f32_e64 s[10:11], s23, v32
	v_div_scale_f32 v36, s[6:7], 1.0, v29, 1.0
	v_mul_f32_e32 v33, v34, v40
	v_fma_f32 v46, -v11, v0, v30
	v_cndmask_b32_e64 v32, v32, v43, s[10:11]
	v_div_scale_f32 v38, s[8:9], 1.0, v28, 1.0
	v_mul_f32_e32 v44, v36, v41
	v_fma_f32 v47, -v31, v33, v34
	v_fmac_f32_e32 v0, v46, v39
	v_rsq_f32_e32 v32, v32
	v_mul_f32_e32 v45, v38, v42
	v_fma_f32 v43, -v35, v44, v36
	v_fmac_f32_e32 v33, v47, v40
	v_fma_f32 v11, -v11, v0, v30
	v_fma_f32 v48, -v37, v45, v38
	v_fmac_f32_e32 v44, v43, v41
	v_fma_f32 v30, -v31, v33, v34
	v_div_fmas_f32 v0, v11, v39, v0
	s_mov_b64 vcc, s[0:1]
	v_fmac_f32_e32 v45, v48, v42
	v_fma_f32 v31, -v35, v44, v36
	v_div_fixup_f32 v27, v0, v27, 1.0
	v_div_fmas_f32 v0, v30, v40, v33
	s_mov_b64 vcc, s[6:7]
	v_fma_f32 v34, -v37, v45, v38
	v_div_fixup_f32 v26, v0, v26, 1.0
	v_mul_f32_e32 v0, 0x45800000, v32
	v_div_fmas_f32 v11, v31, v41, v44
	s_mov_b64 vcc, s[8:9]
	v_pk_mul_f32 v[24:25], v[26:27], v[24:25]
	v_cndmask_b32_e64 v0, v32, v0, s[10:11]
	v_div_fixup_f32 v27, v11, v29, 1.0
	v_div_fmas_f32 v11, v34, v42, v45
	v_pk_mul_f32 v[22:23], v[22:23], v[0:1] op_sel_hi:[1,0]
	v_pk_mul_f32 v[20:21], v[20:21], v[0:1] op_sel_hi:[1,0]
	v_div_fixup_f32 v26, v11, v28, 1.0
	v_pk_mul_f32 v[12:13], v[12:13], v[22:23]
	v_pk_mul_f32 v[14:15], v[14:15], v[20:21]
	v_pk_mul_f32 v[16:17], v[26:27], v[16:17]
	v_pk_mul_f32 v[12:13], v[12:13], v[24:25]
	v_pk_mul_f32 v[14:15], v[14:15], v[16:17]
	v_cvt_pk_bf16_f32 v12, v12, v13
	v_cvt_pk_bf16_f32 v13, v14, v15
	global_store_dwordx2 v[18:19], v[12:13], off
	s_andn2_b64 exec, exec, s[18:19]
	s_cbranch_execnz .LBB0_552
	s_or_b64 exec, exec, s[18:19]
	s_add_u32 s0, s92, 0x1f700000
	s_addc_u32 s1, s93, 0
	s_add_u32 s6, s92, 0x1d500000
	s_addc_u32 s7, s93, 0
	s_add_u32 s8, s92, 0x1c500000
	v_lshlrev_b32_e32 v0, 2, v4
	s_addc_u32 s9, s93, 0
	v_and_b32_e32 v4, 60, v0
	s_add_u32 s10, s92, 0x10400000
	v_lshlrev_b32_e32 v0, 2, v3
	v_lshrrev_b32_e32 v5, 4, v5
	s_addc_u32 s11, s93, 0
	v_lshl_add_u32 v3, s2, 5, v0
	s_lshl_b32 s3, s94, 5
	s_mov_b64 s[14:15], 0
	v_mov_b32_e32 v1, 0
	v_mov_b32_e32 v6, 0x3a27c5ac
	s_mov_b32 s16, 0x800000
	s_movk_i32 s17, 0x7fff
; DEVINL float bflo(unsigned u) { return __uint_as_float(u << 16); }
; DEVINL float bfhi(unsigned u) { return __uint_as_float(u & 0xffff0000u); }
; DEVINL void phase4(const Params& p) {
;     ...
;   for (int u = gw; u < T_ * 4; u += nw) {
;     const long t = u >> 2; const int hq = u & 3;
;     const int c = (hq * 4 + (lane >> 4)) * 64 + (lane & 15) * 4;
;     float4 y;
;     {
;       const uint2 y1 = *(const uint2*)((const u16*)(ws + O_YSUM) + t * 1024 + c);
;       const uint2 y2 = *(const uint2*)((const u16*)(ws + O_YB) + t * 1024 + c);
;       y.x = bflo(y1.x) + bflo(y2.x); y.y = bfhi(y1.x) + bfhi(y2.x);
;       y.z = bflo(y1.y) + bflo(y2.y); y.w = bfhi(y1.y) + bfhi(y2.y);
;     }
;     float mu = allred16(y.x + y.y + y.z + y.w) * (1.f / 64.f);
;     float d0 = y.x - mu, d1 = y.y - mu, d2 = y.z - mu, d3 = y.w - mu;
;     float var = allred16(d0 * d0 + d1 * d1 + d2 * d2 + d3 * d3) * (1.f / 64.f);
;     const float rstd = rsqrtf(var + 64e-5f);
;     float4 lg = *(const float4*)(p.rw_ln_g + c);
;     float4 lb = *(const float4*)(p.rw_ln_b + c);
;     uint2 bo = *(const uint2*)((const u16*)(ws + O_BONUS) + t * 1024 + c);
;     uint2 gg = *(const uint2*)((const u16*)(ws + O_GRW) + t * 1024 + c);
;     float r0 = (d0 * rstd * lg.x + lb.x + bflo(bo.x)) * bflo(gg.x);
;     float r1 = (d1 * rstd * lg.y + lb.y + bfhi(bo.x)) * bfhi(gg.x);
;     float r2 = (d2 * rstd * lg.z + lb.z + bflo(bo.y)) * bflo(gg.y);
;     float r3 = (d3 * rstd * lg.w + lb.w + bfhi(bo.y)) * bfhi(gg.y);
;     *(uint2*)((u16*)(ws + O_YRW) + t * 1024 + c) = make_uint2(pk2(r0, r1), pk2(r2, r3));
;   }
.LBB0_554:
	v_ashrrev_i32_e32 v8, 2, v2
	v_and_or_b32 v0, v3, 12, v5
	v_ashrrev_i32_e32 v9, 31, v8
	v_lshl_or_b32 v7, v0, 6, v4
	v_lshlrev_b64 v[16:17], 11, v[8:9]
	v_lshlrev_b32_e32 v0, 1, v7
	v_lshl_add_u64 v[18:19], s[34:35], 0, v[16:17]
	v_lshl_add_u64 v[20:21], s[0:1], 0, v[16:17]
	v_lshl_add_u64 v[22:23], s[6:7], 0, v[16:17]
	v_lshl_add_u64 v[24:25], s[8:9], 0, v[16:17]
	v_lshlrev_b32_e32 v7, 2, v7
	v_lshl_add_u64 v[18:19], v[18:19], 0, v[0:1]
	v_lshl_add_u64 v[20:21], v[20:21], 0, v[0:1]
	v_lshl_add_u64 v[22:23], v[22:23], 0, v[0:1]
	v_lshl_add_u64 v[24:25], v[24:25], 0, v[0:1]
	global_load_dwordx4 v[8:11], v7, s[64:65] nt
	global_load_dwordx4 v[12:15], v7, s[66:67] nt
	s_nop 0
	global_load_dwordx2 v[18:19], v[18:19], off nt
	s_nop 0
	global_load_dwordx2 v[20:21], v[20:21], off nt
	s_nop 0
	global_load_dwordx2 v[22:23], v[22:23], off nt
	s_nop 0
	global_load_dwordx2 v[24:25], v[24:25], off nt
	v_lshl_add_u64 v[16:17], s[10:11], 0, v[16:17]
	v_lshl_add_u64 v[16:17], v[16:17], 0, v[0:1]
	v_add_u32_e32 v2, s60, v2
	v_cmp_lt_i32_e32 vcc, s17, v2
	s_or_b64 s[14:15], vcc, s[14:15]
	v_add_u32_e32 v3, s3, v3
	s_waitcnt vmcnt(3)
	v_lshlrev_b32_e32 v26, 16, v18
	s_waitcnt vmcnt(2)
	v_lshlrev_b32_e32 v28, 16, v20
	v_and_b32_e32 v27, 0xffff0000, v18
	v_and_b32_e32 v29, 0xffff0000, v20
	v_lshlrev_b32_e32 v18, 16, v19
	v_lshlrev_b32_e32 v20, 16, v21
	v_and_b32_e32 v19, 0xffff0000, v19
	v_and_b32_e32 v21, 0xffff0000, v21
	v_pk_add_f32 v[18:19], v[18:19], v[20:21]
	v_pk_add_f32 v[20:21], v[26:27], v[28:29]
	s_waitcnt vmcnt(1)
	v_lshlrev_b32_e32 v30, 16, v22
	v_add_f32_e32 v0, v20, v21
	v_add_f32_e32 v0, v0, v18
	v_add_f32_e32 v0, v19, v0
	v_and_b32_e32 v31, 0xffff0000, v22
	v_lshlrev_b32_e32 v22, 16, v23
	v_add_f32_dpp v0, v0, v0 quad_perm:[1,0,3,2] row_mask:0xf bank_mask:0xf bound_ctrl:1
	v_and_b32_e32 v23, 0xffff0000, v23
	s_waitcnt vmcnt(0)
	v_lshlrev_b32_e32 v32, 16, v24
	v_add_f32_dpp v0, v0, v0 quad_perm:[2,3,0,1] row_mask:0xf bank_mask:0xf bound_ctrl:1
	v_and_b32_e32 v33, 0xffff0000, v24
	v_lshlrev_b32_e32 v24, 16, v25
	v_add_f32_dpp v0, v0, v0 row_half_mirror row_mask:0xf bank_mask:0xf bound_ctrl:1
	v_and_b32_e32 v25, 0xffff0000, v25
	s_nop 0
	v_add_f32_dpp v0, v0, v0 row_mirror row_mask:0xf bank_mask:0xf bound_ctrl:1
	v_mul_f32_e32 v0, 0x3c800000, v0
	v_pk_add_f32 v[20:21], v[20:21], v[0:1] op_sel_hi:[1,0] neg_lo:[0,1] neg_hi:[0,1]
	v_pk_add_f32 v[18:19], v[18:19], v[0:1] op_sel_hi:[1,0] neg_lo:[0,1] neg_hi:[0,1]
	v_pk_mul_f32 v[26:27], v[20:21], v[20:21]
	v_pk_mul_f32 v[28:29], v[18:19], v[18:19]
	v_add_f32_e32 v0, v26, v27
	v_add_f32_e32 v0, v28, v0
	v_add_f32_e32 v0, v29, v0
	s_nop 1
	v_add_f32_dpp v0, v0, v0 quad_perm:[1,0,3,2] row_mask:0xf bank_mask:0xf bound_ctrl:1
	s_nop 1
	v_add_f32_dpp v0, v0, v0 quad_perm:[2,3,0,1] row_mask:0xf bank_mask:0xf bound_ctrl:1
	s_nop 1
	v_add_f32_dpp v0, v0, v0 row_half_mirror row_mask:0xf bank_mask:0xf bound_ctrl:1
	s_nop 1
	v_add_f32_dpp v0, v0, v0 row_mirror row_mask:0xf bank_mask:0xf bound_ctrl:1
	v_fmamk_f32 v0, v0, 0x3c800000, v6
	v_mul_f32_e32 v7, 0x4b800000, v0
	v_cmp_gt_f32_e32 vcc, s16, v0
	s_nop 1
	v_cndmask_b32_e32 v0, v0, v7, vcc
	v_rsq_f32_e32 v0, v0
	s_nop 0
	v_mul_f32_e32 v7, 0x45800000, v0
	v_cndmask_b32_e32 v0, v0, v7, vcc
	v_pk_mul_f32 v[20:21], v[20:21], v[0:1] op_sel_hi:[1,0]
	v_pk_mul_f32 v[18:19], v[18:19], v[0:1] op_sel_hi:[1,0]
	v_pk_fma_f32 v[8:9], v[8:9], v[20:21], v[12:13]
	v_pk_fma_f32 v[10:11], v[10:11], v[18:19], v[14:15]
	v_pk_add_f32 v[8:9], v[8:9], v[30:31]
	v_pk_add_f32 v[10:11], v[10:11], v[22:23]
	v_pk_mul_f32 v[8:9], v[8:9], v[32:33]
	v_pk_mul_f32 v[10:11], v[10:11], v[24:25]
	v_cvt_pk_bf16_f32 v8, v8, v9
	v_cvt_pk_bf16_f32 v9, v10, v11
	global_store_dwordx2 v[16:17], v[8:9], off
	s_andn2_b64 exec, exec, s[14:15]
	s_cbranch_execnz .LBB0_554
